# SSD prompt loop: scores+cross MFMA stage with LDS fragment reads through a 5-buffer ring and counted lgkmcnt (same k order)
# speedup vs baseline: 1.0023x; 1.0023x over previous
; __device__ __forceinline__ float ex2(float x) { return __builtin_amdgcn_exp2f(x); }
; template <int DK, int MODE>
; __device__ void rec_prompt_item(const Params& p, const int item, unsigned char* smem) {
;     ...
; #pragma unroll KUNR
;     for (int ks = 0; ks < KS; ++ks) {
;       const bf16x8 a = *(const bf16x8*)(Qs + (16 * fi + l15) * QS + ks * 64 + g * 16);
;       bf16x8 bk[2], bs[2];
; #pragma unroll
;       for (int x = 0; x < 2; ++x) {
;         bk[x] = *(const bf16x8*)(Ks + (16 * (fe0 + x) + l15) * QS + ks * 64 + g * 16);
;         bs[x] = *(const bf16x8*)(STs + (16 * (fe0 + x) + l15) * QS + ks * 64 + g * 16);
;       }
; #pragma unroll
;       for (int x = 0; x < 2; ++x) {
;         sc[x] = __builtin_amdgcn_mfma_f32_16x16x32_bf16(a, bk[x], sc[x], 0, 0, 0);
;         cr[x] = __builtin_amdgcn_mfma_f32_16x16x32_bf16(a, bs[x], cr[x], 0, 0, 0);
;       }
;     }
;     float ci[4];
; #pragma unroll
;     for (int r = 0; r < 4; ++r) ci[r] = cumS[16 * fi + 4 * g + r];
; #pragma unroll
;     for (int x = 0; x < 2; ++x) {
;       const int fj = fe0 + x;
;       const int j = 16 * fj + l15;
;       const float cj = cumS[j], uj = uS[j];
; #pragma unroll
;       for (int r = 0; r < 4; ++r) {
;         const int i = 16 * fi + 4 * g + r;
;         float v = 0.f;
;         if (j <= i) v = sc[x][r] * ex2(ci[r] - cj) * uj;
;         *(u16*)(Ps + i * PS + j * 2) = f2bf(v);
;       }
;     }
;     {
;       const float atot = ex2(cumS[63]);
; #pragma unroll
;       for (int mf = 0; mf < MF; ++mf)
; #pragma unroll
;         for (int nf = 0; nf < 4; ++nf)
; #pragma unroll
;           for (int r = 0; r < 4; ++r) S[mf][nf][r] *= atot;
; #pragma unroll
;       for (int ks = 0; ks < 2; ++ks) {
;         bf16x8 af[MF], bfv[4];
; #pragma unroll
;         for (int mf = 0; mf < MF; ++mf) af[mf] = trfrag(Ks, QS, 32 * ks, dw + 16 * mf, lane);
; #pragma unroll
;         for (int nf = 0; nf < 4; ++nf) bfv[nf] = trfrag(Vts, VS, 32 * ks, 16 * nf, lane);
; #pragma unroll
;         for (int mf = 0; mf < MF; ++mf)
; #pragma unroll
;           for (int nf = 0; nf < 4; ++nf)
;             S[mf][nf] = __builtin_amdgcn_mfma_f32_16x16x32_bf16(af[mf], bfv[nf], S[mf][nf], 0, 0, 0);
;       }
;     }
.LBB0_1715:
	v_add_u32_e32 v235, v169, v167
	ds_read_b128 v[56:59], v191
	ds_read_b128 v[60:63], v192 offset:18432
	ds_read_b128 v[64:67], v192 offset:36864
	ds_read_b128 v[68:71], v193 offset:18432
	ds_read_b128 v[236:239], v193 offset:36864
	ds_read_b128 v[240:243], v191 offset:64
	ds_read_b128 v[244:247], v192 offset:18496
	ds_read_b128 v[248:251], v192 offset:36928
	ds_read_b128 v[144:147], v193 offset:18496
	s_waitcnt lgkmcnt(7)
	v_mfma_f32_16x16x32_bf16 v[60:63], v[56:59], v[60:63], 0
	s_waitcnt lgkmcnt(6)
	v_mfma_f32_16x16x32_bf16 v[64:67], v[56:59], v[64:67], 0
	s_waitcnt lgkmcnt(5)
	v_mfma_f32_16x16x32_bf16 v[68:71], v[56:59], v[68:71], 0
	s_waitcnt lgkmcnt(4)
	v_mfma_f32_16x16x32_bf16 v[56:59], v[56:59], v[236:239], 0
	ds_read_b128 v[236:239], v193 offset:36928
	s_waitcnt lgkmcnt(3)
	v_mfma_f32_16x16x32_bf16 v[60:63], v[240:243], v[244:247], v[60:63]
	ds_read_b128 v[244:247], v191 offset:128
	s_waitcnt lgkmcnt(3)
	v_mfma_f32_16x16x32_bf16 v[64:67], v[240:243], v[248:251], v[64:67]
	ds_read_b128 v[248:251], v192 offset:18560
	s_waitcnt lgkmcnt(3)
	v_mfma_f32_16x16x32_bf16 v[68:71], v[240:243], v[144:147], v[68:71]
	ds_read_b128 v[144:147], v192 offset:36992
	s_waitcnt lgkmcnt(3)
	v_mfma_f32_16x16x32_bf16 v[56:59], v[240:243], v[236:239], v[56:59]
	ds_read_b128 v[236:239], v193 offset:18560
	ds_read_b128 v[240:243], v193 offset:36992
	s_waitcnt lgkmcnt(3)
	v_mfma_f32_16x16x32_bf16 v[60:63], v[244:247], v[248:251], v[60:63]
	ds_read_b128 v[248:251], v191 offset:192
	s_waitcnt lgkmcnt(3)
	v_mfma_f32_16x16x32_bf16 v[64:67], v[244:247], v[144:147], v[64:67]
	ds_read_b128 v[144:147], v192 offset:37056
	s_waitcnt lgkmcnt(3)
	v_mfma_f32_16x16x32_bf16 v[68:71], v[244:247], v[236:239], v[68:71]
	ds_read_b128 v[236:239], v192 offset:18624
	s_waitcnt lgkmcnt(3)
	v_mfma_f32_16x16x32_bf16 v[56:59], v[244:247], v[240:243], v[56:59]
	ds_read_b128 v[240:243], v193 offset:18624
	ds_read_b128 v[244:247], v193 offset:37056
	s_waitcnt lgkmcnt(2)
	v_mfma_f32_16x16x32_bf16 v[236:239], v[248:251], v[236:239], v[60:63]
	v_mfma_f32_16x16x32_bf16 v[60:63], v[248:251], v[144:147], v[64:67]
	s_nop 2
	ds_read_b128 v[64:67], v195
	ds_read_b32 v135, v162
	ds_read_b32 v137, v163
	s_waitcnt lgkmcnt(1)
	v_sub_f32_e32 v139, v64, v135
	v_exp_f32_e32 v139, v139
	v_mfma_f32_16x16x32_bf16 v[68:71], v[248:251], v[240:243], v[68:71]
	v_mul_f32_e32 v139, v236, v139
	s_waitcnt lgkmcnt(0)
	v_mul_f32_e32 v139, v137, v139
	v_cvt_pk_bf16_f32 v139, v139, s0
	v_cndmask_b32_e64 v139, v139, 0, s[6:7]
	ds_write_b16 v196, v139
	v_sub_f32_e32 v139, v65, v135
	v_exp_f32_e32 v139, v139
	v_mfma_f32_16x16x32_bf16 v[56:59], v[248:251], v[244:247], v[56:59]
	v_mul_f32_e32 v139, v237, v139
	v_mul_f32_e32 v139, v137, v139
	v_cvt_pk_bf16_f32 v139, v139, s0
	v_cndmask_b32_e64 v139, v139, 0, s[8:9]
	ds_write_b16 v196, v139 offset:144
	v_sub_f32_e32 v139, v66, v135
	v_sub_f32_e32 v135, v67, v135
	v_exp_f32_e32 v139, v139
	v_exp_f32_e32 v135, v135
	v_mul_f32_e32 v139, v238, v139
	v_mul_f32_e32 v135, v239, v135
	v_mul_f32_e32 v139, v137, v139
	v_mul_f32_e32 v135, v137, v135
	v_cvt_pk_bf16_f32 v139, v139, s0
	v_cvt_pk_bf16_f32 v135, v135, s0
	v_cndmask_b32_e64 v139, v139, 0, s[10:11]
	v_cndmask_b32_e64 v135, v135, 0, s[12:13]
	ds_write_b16 v196, v139 offset:288
	ds_write_b16 v196, v135 offset:432
	ds_read_b32 v135, v164
	ds_read_b32 v137, v165
	s_waitcnt lgkmcnt(1)
	v_sub_f32_e32 v139, v64, v135
	v_exp_f32_e32 v139, v139
	s_nop 0
	v_mul_f32_e32 v68, v68, v139
	s_waitcnt lgkmcnt(0)
	v_mul_f32_e32 v68, v137, v68
	v_cvt_pk_bf16_f32 v68, v68, s0
	v_cndmask_b32_e64 v68, v68, 0, s[14:15]
	ds_write_b16 v197, v68
	v_sub_f32_e32 v68, v65, v135
	v_exp_f32_e32 v68, v68
	v_exp_f32_e32 v65, v65
	v_mul_f32_e32 v68, v69, v68
	v_mul_f32_e32 v68, v137, v68
	v_cvt_pk_bf16_f32 v68, v68, s0
	v_cndmask_b32_e64 v68, v68, 0, s[16:17]
	ds_write_b16 v197, v68 offset:144
	v_sub_f32_e32 v68, v66, v135
	v_exp_f32_e32 v68, v68
	v_exp_f32_e32 v66, v66
	v_mul_f32_e32 v68, v70, v68
	v_mul_f32_e32 v68, v137, v68
	v_cvt_pk_bf16_f32 v68, v68, s0
	v_cndmask_b32_e64 v68, v68, 0, s[18:19]
	ds_write_b16 v197, v68 offset:288
	v_sub_f32_e32 v68, v67, v135
	v_exp_f32_e32 v68, v68
	v_exp_f32_e32 v67, v67
	v_mul_f32_e32 v68, v71, v68
	v_mul_f32_e32 v68, v137, v68
	v_cvt_pk_bf16_f32 v68, v68, s0
	v_cndmask_b32_e64 v68, v68, 0, s[20:21]
	ds_write_b16 v197, v68 offset:432
	ds_read_b32 v68, v189
	s_waitcnt lgkmcnt(0)
	v_exp_f32_e32 v68, v68
	s_nop 0
	v_pk_mul_f32 v[54:55], v[54:55], v[68:69] op_sel_hi:[1,0]
	v_pk_mul_f32 v[52:53], v[52:53], v[68:69] op_sel_hi:[1,0]
	v_pk_mul_f32 v[50:51], v[50:51], v[68:69] op_sel_hi:[1,0]
	v_pk_mul_f32 v[48:49], v[48:49], v[68:69] op_sel_hi:[1,0]
	v_pk_mul_f32 v[46:47], v[46:47], v[68:69] op_sel_hi:[1,0]
	v_pk_mul_f32 v[44:45], v[44:45], v[68:69] op_sel_hi:[1,0]
	v_pk_mul_f32 v[42:43], v[42:43], v[68:69] op_sel_hi:[1,0]
	v_pk_mul_f32 v[40:41], v[40:41], v[68:69] op_sel_hi:[1,0]
	ds_read_b64_tr_b16 v[68:69], v198 offset:18432
	ds_read_b64_tr_b16 v[70:71], v198 offset:19584
	ds_read_b64_tr_b16 v[146:147], v199 offset:640
	ds_read_b64_tr_b16 v[144:145], v199
	ds_read_b64_tr_b16 v[236:237], v199 offset:32
	ds_read_b64_tr_b16 v[238:239], v199 offset:672
	ds_read_b64_tr_b16 v[240:241], v199 offset:64
	ds_read_b64_tr_b16 v[242:243], v199 offset:704
	ds_read_b64_tr_b16 v[244:245], v199 offset:96
	ds_read_b64_tr_b16 v[246:247], v199 offset:736
	s_waitcnt lgkmcnt(6)
	v_mfma_f32_16x16x32_bf16 v[52:55], v[68:71], v[144:147], v[52:55]
	s_waitcnt lgkmcnt(4)
	v_mfma_f32_16x16x32_bf16 v[48:51], v[68:71], v[236:239], v[48:51]
	s_waitcnt lgkmcnt(2)
	v_mfma_f32_16x16x32_bf16 v[144:147], v[68:71], v[240:243], v[44:47]
	s_waitcnt lgkmcnt(0)
	v_mfma_f32_16x16x32_bf16 v[68:71], v[68:71], v[244:247], v[40:43]
	ds_read_b64_tr_b16 v[236:237], v198 offset:27648
	ds_read_b64_tr_b16 v[238:239], v198 offset:28800
	s_nop 0
	ds_read_b64_tr_b16 v[40:41], v199 offset:5120
	ds_read_b64_tr_b16 v[42:43], v199 offset:5760
	ds_read_b64_tr_b16 v[44:45], v199 offset:5152
	ds_read_b64_tr_b16 v[46:47], v199 offset:5792
	ds_read_b64_tr_b16 v[240:241], v199 offset:5184
	ds_read_b64_tr_b16 v[242:243], v199 offset:5824
	ds_read_b64_tr_b16 v[244:245], v199 offset:5216
	ds_read_b64_tr_b16 v[246:247], v199 offset:5856
	s_waitcnt lgkmcnt(0)
	s_barrier
; __device__ __forceinline__ float bf2f(u16 h) { return __uint_as_float(((uint32_t)h) << 16); }
; __device__ __forceinline__ float ex2(float x) { return __builtin_amdgcn_exp2f(x); }
; __device__ __forceinline__ float silu(float x) { return x * __builtin_amdgcn_rcpf(1.0f + __expf(-x)); }
; template <int DK, int MODE>
; __device__ void rec_prompt_item(const Params& p, const int item, unsigned char* smem) {
;     ...
;     f32x4 in[2];
; #pragma unroll
;     for (int x = 0; x < 2; ++x) in[x] = (f32x4){0.f, 0.f, 0.f, 0.f};
; #pragma unroll
;     for (int ks = 0; ks < 2; ++ks) {
;       const bf16x8 a = *(const bf16x8*)(Ps + (16 * fi + l15) * PS + ks * 64 + g * 16);
;       bf16x8 bv[2];
; #pragma unroll
;       for (int x = 0; x < 2; ++x) bv[x] = trfrag(Vs, VS, 32 * ks, 16 * (fe0 + x), lane);
; #pragma unroll
;       for (int x = 0; x < 2; ++x) in[x] = __builtin_amdgcn_mfma_f32_16x16x32_bf16(a, bv[x], in[x], 0, 0, 0);
;     }
;     {
;       float ss[4] = {0.f, 0.f, 0.f, 0.f};
;       u16* aout = (u16*)(p.ws + OFF_A2);
;       float* parts = (float*)(p.ws + OFF_PARTS);
; #pragma unroll
;       for (int x = 0; x < 2; ++x) {
;         const int e = 16 * (fe0 + x) + l15;
;         const float gn = gnv[x];
;         const int ocol = (MODE == 0) ? (h * 512 + s * 64 + e) : (h * 64 + e);
; #pragma unroll
;         for (int r = 0; r < 4; ++r) {
;           const int i = 16 * fi + 4 * g + r;
;           float o = in[x][r] + cr[x][r] * ex2(ci[r]);
;           const float gv = bf2f(gzc[x][r]);
;           float val;
;           if (MODE == 0) {
;             ss[r] += o * o;
;             val = o * gn * silu(gv);
;           } else {
;             const float xs = bf2f(*(const u16*)(Vs + i * VS + e * 2));
;             const float y = o + xs * dsk;
;             const float gg = y * silu(gv);
;             ss[r] += gg * gg;
;             val = gg * gn;
;           }
;           *(u16*)((char*)aout + (size_t)r0 * 4096 + 32 * x + aoff[r]) = f2bf(val);
;         }
;       }
; #pragma unroll
;       for (int r = 0; r < 4; ++r) {
;         const float v = row16_sum(ss[r]);
;         if (l15 == 0) {
;           const int i = 16 * fi + 4 * g + r;
;           const int slot = (MODE == 0) ? (h * 16 + s * 2 + (w & 1)) : ((h >> 2) * 8 + (h & 3) * 2 + (w & 1));
;           parts[(size_t)(r0 + i) * 64 + slot] = v;
;         }
	v_mfma_f32_16x16x32_bf16 v[44:47], v[236:239], v[44:47], v[48:51]
	v_mfma_f32_16x16x32_bf16 v[48:51], v[236:239], v[244:247], v[68:71]
	s_nop 2
	ds_read_b128 v[68:71], v200
	v_mfma_f32_16x16x32_bf16 v[40:43], v[236:239], v[40:43], v[52:55]
	v_mfma_f32_16x16x32_bf16 v[52:55], v[236:239], v[240:243], v[144:147]
	v_add_u32_e32 v236, v166, v167
	v_add_u32_e32 v237, v166, v168
	s_nop 0
	ds_read_b64_tr_b16 v[144:145], v236 offset:55296
	ds_read_b64_tr_b16 v[146:147], v236 offset:55936
	ds_read_b64_tr_b16 v[238:239], v237 offset:55296
	ds_read_b64_tr_b16 v[240:241], v237 offset:55936
	s_waitcnt lgkmcnt(2)
	v_mfma_f32_16x16x32_bf16 v[144:147], v[68:71], v[144:147], 0
	s_waitcnt lgkmcnt(0)
	v_mfma_f32_16x16x32_bf16 v[68:71], v[68:71], v[238:241], 0
	ds_read_b128 v[240:243], v200 offset:64
	ds_read_b64_tr_b16 v[244:245], v235 offset:55296
	ds_read_b64_tr_b16 v[246:247], v235 offset:55936
	v_add_u32_e32 v238, v169, v168
	ds_read_b64_tr_b16 v[248:249], v238 offset:55296
	ds_read_b64_tr_b16 v[250:251], v238 offset:55936
	v_exp_f32_e32 v239, v64
	v_lshlrev_b32_e32 v64, 16, v134
	ds_read_u16 v134, v201 offset:55296
	s_waitcnt lgkmcnt(3)
	v_mfma_f32_16x16x32_bf16 v[144:147], v[240:243], v[244:247], v[144:147]
	s_waitcnt lgkmcnt(0)
	v_lshlrev_b32_e32 v134, 16, v134
	v_mfma_f32_16x16x32_bf16 v[68:71], v[240:243], v[248:251], v[68:71]
	s_nop 4
	v_fma_f32 v60, v60, v239, v144
	v_fmac_f32_e32 v60, v74, v134
	v_mul_f32_e32 v134, 0xbfb8aa3b, v64
	v_exp_f32_e32 v134, v134
	v_fmac_f32_e32 v147, v63, v67
	v_fma_f32 v56, v56, v239, v68
	v_lshlrev_b32_e32 v68, 16, v234
	v_add_f32_e32 v134, 1.0, v134
	v_rcp_f32_e32 v134, v134
	v_fmac_f32_e32 v71, v59, v67
	v_mul_f32_e32 v64, v134, v64
	v_mul_f32_e32 v244, v64, v60
	ds_read_u16 v64, v201 offset:55456
	v_lshl_add_u64 v[134:135], v[112:113], 0, s[24:25]
	v_mul_f32_e32 v60, v203, v244
	v_add_co_u32_e32 v240, vcc, s63, v134
	v_cvt_pk_bf16_f32 v60, v60, s0
	s_nop 0
	v_addc_co_u32_e32 v241, vcc, 0, v135, vcc
	global_store_short v[240:241], v60, off
	v_fma_f32 v60, v61, v65, v145
	v_lshlrev_b32_e32 v61, 16, v136
	s_waitcnt lgkmcnt(0)
	v_lshlrev_b32_e32 v64, 16, v64
	v_fmac_f32_e32 v60, v74, v64
	v_mul_f32_e32 v64, 0xbfb8aa3b, v61
	v_exp_f32_e32 v64, v64
	v_lshl_add_u64 v[136:137], v[108:109], 0, s[24:25]
	v_add_co_u32_e32 v144, vcc, s63, v136
	v_add_f32_e32 v64, 1.0, v64
	v_rcp_f32_e32 v64, v64
	v_addc_co_u32_e32 v145, vcc, 0, v137, vcc
	v_mul_f32_e32 v61, v64, v61
	v_mul_f32_e32 v64, v61, v60
	v_mul_f32_e32 v60, v203, v64
	v_cvt_pk_bf16_f32 v60, v60, s0
	global_store_short v[144:145], v60, off
	v_fma_f32 v60, v62, v66, v146
	ds_read_u16 v62, v201 offset:55616
	v_lshlrev_b32_e32 v61, 16, v138
	v_lshl_add_u64 v[138:139], v[102:103], 0, s[24:25]
	v_add_co_u32_e32 v242, vcc, s63, v138
	s_waitcnt lgkmcnt(0)
	v_lshlrev_b32_e32 v62, 16, v62
	v_fmac_f32_e32 v60, v74, v62
	v_mul_f32_e32 v62, 0xbfb8aa3b, v61
	v_exp_f32_e32 v62, v62
	v_addc_co_u32_e32 v243, vcc, 0, v139, vcc
	v_add_f32_e32 v62, 1.0, v62
	v_rcp_f32_e32 v62, v62
	s_nop 0
	v_mul_f32_e32 v61, v62, v61
	v_mul_f32_e32 v62, v61, v60
	ds_read_u16 v61, v201 offset:55776
	v_mul_f32_e32 v60, v203, v62
	v_cvt_pk_bf16_f32 v60, v60, s0
	global_store_short v[242:243], v60, off
	v_lshlrev_b32_e32 v60, 16, v140
	s_waitcnt lgkmcnt(0)
	v_lshlrev_b32_e32 v61, 16, v61
	v_fmac_f32_e32 v147, v74, v61
	v_mul_f32_e32 v61, 0xbfb8aa3b, v60
	v_exp_f32_e32 v61, v61
	v_lshl_add_u64 v[140:141], v[94:95], 0, s[24:25]
	v_add_f32_e32 v61, 1.0, v61
	v_rcp_f32_e32 v61, v61
	s_nop 0
	v_mul_f32_e32 v60, v61, v60
	v_mul_f32_e32 v63, v60, v147
	v_mul_f32_e32 v60, v203, v63
	v_cvt_pk_bf16_f32 v146, v60, s0
	v_add_co_u32_e32 v60, vcc, s63, v140
	s_nop 1
	v_addc_co_u32_e32 v61, vcc, 0, v141, vcc
	global_store_short v[60:61], v146, off
	ds_read_u16 v146, v202 offset:55296
	s_waitcnt lgkmcnt(0)
	v_lshlrev_b32_e32 v146, 16, v146
	v_fmac_f32_e32 v56, v74, v146
	v_mul_f32_e32 v146, 0xbfb8aa3b, v68
	v_exp_f32_e32 v146, v146
	s_nop 0
	v_add_f32_e32 v146, 1.0, v146
	v_rcp_f32_e32 v146, v146
	s_nop 0
	v_mul_f32_e32 v68, v146, v68
	v_mul_f32_e32 v56, v68, v56
	v_mul_f32_e32 v68, v56, v56
	v_mul_f32_e32 v56, v204, v56
	v_cvt_pk_bf16_f32 v56, v56, s0
	global_store_short v[240:241], v56, off offset:32
	v_fma_f32 v56, v57, v65, v69
	ds_read_u16 v65, v202 offset:55456
	v_lshlrev_b32_e32 v57, 16, v233
	v_fmac_f32_e32 v68, v244, v244
	s_waitcnt lgkmcnt(0)
	v_lshlrev_b32_e32 v65, 16, v65
	v_fmac_f32_e32 v56, v74, v65
	v_mul_f32_e32 v65, 0xbfb8aa3b, v57
	v_exp_f32_e32 v65, v65
	s_nop 0
	v_add_f32_e32 v65, 1.0, v65
	v_rcp_f32_e32 v65, v65
	s_nop 0
	v_mul_f32_e32 v57, v65, v57
	v_mul_f32_e32 v65, v57, v56
	v_mul_f32_e32 v56, v204, v65
	v_cvt_pk_bf16_f32 v56, v56, s0
	global_store_short v[144:145], v56, off offset:32
	v_fma_f32 v56, v58, v66, v70
	ds_read_u16 v58, v202 offset:55616
	v_lshlrev_b32_e32 v57, 16, v232
	s_waitcnt lgkmcnt(0)
	v_lshlrev_b32_e32 v58, 16, v58
	v_fmac_f32_e32 v56, v74, v58
	v_mul_f32_e32 v58, 0xbfb8aa3b, v57
	v_exp_f32_e32 v58, v58
	s_nop 0
	v_add_f32_e32 v58, 1.0, v58
	v_rcp_f32_e32 v58, v58
	s_nop 0
	v_mul_f32_e32 v57, v58, v57
	v_mul_f32_e32 v58, v57, v56
	ds_read_u16 v57, v202 offset:55776
	v_mul_f32_e32 v56, v204, v58
	v_cvt_pk_bf16_f32 v56, v56, s0
	global_store_short v[242:243], v56, off offset:32
	v_lshlrev_b32_e32 v56, 16, v231
	s_waitcnt lgkmcnt(0)
	v_lshlrev_b32_e32 v57, 16, v57
	v_fmac_f32_e32 v71, v74, v57
	v_mul_f32_e32 v57, 0xbfb8aa3b, v56
	v_exp_f32_e32 v57, v57
	s_nop 0
	v_add_f32_e32 v57, 1.0, v57
	v_rcp_f32_e32 v57, v57
	s_nop 0
	v_mul_f32_e32 v56, v57, v56
	v_mul_f32_e32 v59, v56, v71
	v_mul_f32_e32 v56, v204, v59
	v_cvt_pk_bf16_f32 v56, v56, s0
	global_store_short v[60:61], v56, off offset:32
	s_nop 0
	v_add_f32_dpp v56, v68, v68 quad_perm:[1,0,3,2] row_mask:0xf bank_mask:0xf bound_ctrl:1
	s_nop 1
	v_add_f32_dpp v56, v56, v56 quad_perm:[2,3,0,1] row_mask:0xf bank_mask:0xf bound_ctrl:1
	s_nop 1
	v_add_f32_dpp v60, v56, v56 row_ror:4 row_mask:0xf bank_mask:0xf bound_ctrl:1
	v_lshl_add_u64 v[56:57], v[114:115], 0, s[24:25]
	s_nop 0
	v_mov_b32_dpp v61, v60 row_ror:8 row_mask:0xf bank_mask:0xf bound_ctrl:1
	s_and_saveexec_b64 s[48:49], s[4:5]
	s_cbranch_execz .LBB0_1717
	v_add_f32_e32 v60, v60, v61
	global_store_dword v[56:57], v60, off offset:-512

; __device__ __forceinline__ float ex2(float x) { return __builtin_amdgcn_exp2f(x); }
; template <int DK, int MODE>
; __device__ void rec_prompt_item(const Params& p, const int item, unsigned char* smem) {
;     ...
; #pragma unroll KUNR
;     for (int ks = 0; ks < KS; ++ks) {
;       const bf16x8 a = *(const bf16x8*)(Qs + (16 * fi + l15) * QS + ks * 64 + g * 16);
;       bf16x8 bk[2], bs[2];
; #pragma unroll
;       for (int x = 0; x < 2; ++x) {
;         bk[x] = *(const bf16x8*)(Ks + (16 * (fe0 + x) + l15) * QS + ks * 64 + g * 16);
;         bs[x] = *(const bf16x8*)(STs + (16 * (fe0 + x) + l15) * QS + ks * 64 + g * 16);
;       }
; #pragma unroll
;       for (int x = 0; x < 2; ++x) {
;         sc[x] = __builtin_amdgcn_mfma_f32_16x16x32_bf16(a, bk[x], sc[x], 0, 0, 0);
;         cr[x] = __builtin_amdgcn_mfma_f32_16x16x32_bf16(a, bs[x], cr[x], 0, 0, 0);
;       }
;     }
;     float ci[4];
; #pragma unroll
;     for (int r = 0; r < 4; ++r) ci[r] = cumS[16 * fi + 4 * g + r];
; #pragma unroll
;     for (int x = 0; x < 2; ++x) {
;       const int fj = fe0 + x;
;       const int j = 16 * fj + l15;
;       const float cj = cumS[j], uj = uS[j];
; #pragma unroll
;       for (int r = 0; r < 4; ++r) {
;         const int i = 16 * fi + 4 * g + r;
;         float v = 0.f;
;         if (j <= i) v = sc[x][r] * ex2(ci[r] - cj) * uj;
;         *(u16*)(Ps + i * PS + j * 2) = f2bf(v);
;       }
;     }
;     {
;       const float atot = ex2(cumS[63]);
; #pragma unroll
;       for (int mf = 0; mf < MF; ++mf)
; #pragma unroll
;         for (int nf = 0; nf < 4; ++nf)
; #pragma unroll
;           for (int r = 0; r < 4; ++r) S[mf][nf][r] *= atot;
; #pragma unroll
;       for (int ks = 0; ks < 2; ++ks) {
;         bf16x8 af[MF], bfv[4];
; #pragma unroll
;         for (int mf = 0; mf < MF; ++mf) af[mf] = trfrag(Ks, QS, 32 * ks, dw + 16 * mf, lane);
; #pragma unroll
;         for (int nf = 0; nf < 4; ++nf) bfv[nf] = trfrag(Vts, VS, 32 * ks, 16 * nf, lane);
; #pragma unroll
;         for (int mf = 0; mf < MF; ++mf)
; #pragma unroll
;           for (int nf = 0; nf < 4; ++nf)
;             S[mf][nf] = __builtin_amdgcn_mfma_f32_16x16x32_bf16(af[mf], bfv[nf], S[mf][nf], 0, 0, 0);
;       }
;     }
.LBB0_1727:
	ds_read_b128 v[56:59], v191
	ds_read_b128 v[60:63], v192 offset:18432
	ds_read_b128 v[64:67], v192 offset:36864
	ds_read_b128 v[68:71], v193 offset:18432
	ds_read_b128 v[124:127], v193 offset:36864
	ds_read_b128 v[120:123], v191 offset:64
	ds_read_b128 v[128:131], v192 offset:18496
	ds_read_b128 v[144:147], v192 offset:36928
	ds_read_b128 v[244:247], v193 offset:18496
	s_waitcnt lgkmcnt(7)
	v_mfma_f32_16x16x32_bf16 v[60:63], v[56:59], v[60:63], 0
	s_waitcnt lgkmcnt(6)
	v_mfma_f32_16x16x32_bf16 v[64:67], v[56:59], v[64:67], 0
	s_waitcnt lgkmcnt(5)
	v_mfma_f32_16x16x32_bf16 v[68:71], v[56:59], v[68:71], 0
	s_waitcnt lgkmcnt(4)
	v_mfma_f32_16x16x32_bf16 v[56:59], v[56:59], v[124:127], 0
	ds_read_b128 v[124:127], v193 offset:36928
	s_waitcnt lgkmcnt(3)
	v_mfma_f32_16x16x32_bf16 v[60:63], v[120:123], v[128:131], v[60:63]
	ds_read_b128 v[128:131], v191 offset:128
	s_waitcnt lgkmcnt(3)
	v_mfma_f32_16x16x32_bf16 v[64:67], v[120:123], v[144:147], v[64:67]
	ds_read_b128 v[144:147], v192 offset:18560
	s_waitcnt lgkmcnt(3)
	v_mfma_f32_16x16x32_bf16 v[68:71], v[120:123], v[244:247], v[68:71]
	ds_read_b128 v[244:247], v192 offset:36992
	s_waitcnt lgkmcnt(3)
	v_mfma_f32_16x16x32_bf16 v[56:59], v[120:123], v[124:127], v[56:59]
	ds_read_b128 v[124:127], v193 offset:18560
	ds_read_b128 v[120:123], v193 offset:36992
	s_waitcnt lgkmcnt(3)
	v_mfma_f32_16x16x32_bf16 v[60:63], v[128:131], v[144:147], v[60:63]
	ds_read_b128 v[144:147], v191 offset:192
	s_waitcnt lgkmcnt(3)
	v_mfma_f32_16x16x32_bf16 v[64:67], v[128:131], v[244:247], v[64:67]
	ds_read_b128 v[244:247], v192 offset:37056
	s_waitcnt lgkmcnt(3)
	v_mfma_f32_16x16x32_bf16 v[68:71], v[128:131], v[124:127], v[68:71]
	ds_read_b128 v[124:127], v192 offset:18624
	s_waitcnt lgkmcnt(3)
	v_mfma_f32_16x16x32_bf16 v[56:59], v[128:131], v[120:123], v[56:59]
	ds_read_b128 v[120:123], v193 offset:18624
	ds_read_b128 v[128:131], v193 offset:37056
	s_waitcnt lgkmcnt(2)
	v_mfma_f32_16x16x32_bf16 v[124:127], v[144:147], v[124:127], v[60:63]
	v_mfma_f32_16x16x32_bf16 v[60:63], v[144:147], v[244:247], v[64:67]
	s_waitcnt lgkmcnt(1)
	v_mfma_f32_16x16x32_bf16 v[68:71], v[144:147], v[120:123], v[68:71]
	s_waitcnt lgkmcnt(0)
	v_mfma_f32_16x16x32_bf16 v[56:59], v[144:147], v[128:131], v[56:59]
	ds_read_b128 v[64:67], v195
	ds_read_b32 v120, v162
	ds_read_b32 v121, v163
	s_waitcnt lgkmcnt(1)
	v_sub_f32_e32 v122, v64, v120
	v_exp_f32_e32 v122, v122
	s_nop 0
	v_mul_f32_e32 v122, v124, v122
	s_waitcnt lgkmcnt(0)
	v_mul_f32_e32 v122, v121, v122
	v_cvt_pk_bf16_f32 v122, v122, s0
	v_cndmask_b32_e64 v122, v122, 0, s[6:7]
	ds_write_b16 v196, v122
	v_sub_f32_e32 v122, v65, v120
	v_exp_f32_e32 v122, v122
	s_nop 0
	v_mul_f32_e32 v122, v125, v122
	v_mul_f32_e32 v122, v121, v122
	v_cvt_pk_bf16_f32 v122, v122, s0
	v_cndmask_b32_e64 v122, v122, 0, s[8:9]
	ds_write_b16 v196, v122 offset:144
	v_sub_f32_e32 v122, v66, v120
	v_sub_f32_e32 v120, v67, v120
	v_exp_f32_e32 v122, v122
	v_exp_f32_e32 v120, v120
	v_mul_f32_e32 v122, v126, v122
	v_mul_f32_e32 v120, v127, v120
	v_mul_f32_e32 v122, v121, v122
	v_mul_f32_e32 v120, v121, v120
	v_cvt_pk_bf16_f32 v122, v122, s0
	v_cvt_pk_bf16_f32 v120, v120, s0
	v_cndmask_b32_e64 v122, v122, 0, s[10:11]
	v_cndmask_b32_e64 v120, v120, 0, s[12:13]
	ds_write_b16 v196, v122 offset:288
	ds_write_b16 v196, v120 offset:432
	ds_read_b32 v120, v164
	ds_read_b32 v121, v165
	s_waitcnt lgkmcnt(1)
	v_sub_f32_e32 v122, v64, v120
	v_exp_f32_e32 v122, v122
	s_nop 0
	v_mul_f32_e32 v68, v68, v122
	s_waitcnt lgkmcnt(0)
	v_mul_f32_e32 v68, v121, v68
	v_cvt_pk_bf16_f32 v68, v68, s0
	v_cndmask_b32_e64 v68, v68, 0, s[14:15]
	ds_write_b16 v197, v68
	v_sub_f32_e32 v68, v65, v120
	v_exp_f32_e32 v68, v68
	v_exp_f32_e32 v65, v65
	v_mul_f32_e32 v68, v69, v68
	v_mul_f32_e32 v68, v121, v68
	v_cvt_pk_bf16_f32 v68, v68, s0
	v_cndmask_b32_e64 v68, v68, 0, s[16:17]
	ds_write_b16 v197, v68 offset:144
	v_sub_f32_e32 v68, v66, v120
	v_exp_f32_e32 v68, v68
	v_exp_f32_e32 v66, v66
	v_mul_f32_e32 v68, v70, v68
	v_mul_f32_e32 v68, v121, v68
	v_cvt_pk_bf16_f32 v68, v68, s0
	v_cndmask_b32_e64 v68, v68, 0, s[18:19]
	ds_write_b16 v197, v68 offset:288
	v_sub_f32_e32 v68, v67, v120
	v_exp_f32_e32 v68, v68
	v_exp_f32_e32 v67, v67
	v_mul_f32_e32 v68, v71, v68
	v_mul_f32_e32 v68, v121, v68
	v_cvt_pk_bf16_f32 v68, v68, s0
	v_cndmask_b32_e64 v68, v68, 0, s[20:21]
	ds_write_b16 v197, v68 offset:432
	ds_read_b32 v68, v189
	s_waitcnt lgkmcnt(0)
	v_exp_f32_e32 v68, v68
	s_nop 0
	v_pk_mul_f32 v[42:43], v[42:43], v[68:69] op_sel_hi:[1,0]
	v_pk_mul_f32 v[40:41], v[40:41], v[68:69] op_sel_hi:[1,0]
	v_pk_mul_f32 v[46:47], v[46:47], v[68:69] op_sel_hi:[1,0]
	v_pk_mul_f32 v[44:45], v[44:45], v[68:69] op_sel_hi:[1,0]
	v_pk_mul_f32 v[54:55], v[54:55], v[68:69] op_sel_hi:[1,0]
	v_pk_mul_f32 v[52:53], v[52:53], v[68:69] op_sel_hi:[1,0]
	v_pk_mul_f32 v[50:51], v[50:51], v[68:69] op_sel_hi:[1,0]
	v_pk_mul_f32 v[48:49], v[48:49], v[68:69] op_sel_hi:[1,0]
	ds_read_b64_tr_b16 v[68:69], v198 offset:18432
	ds_read_b64_tr_b16 v[70:71], v198 offset:19584
	ds_read_b64_tr_b16 v[122:123], v199 offset:640
	ds_read_b64_tr_b16 v[120:121], v199
	ds_read_b64_tr_b16 v[124:125], v199 offset:32
	ds_read_b64_tr_b16 v[126:127], v199 offset:672
	ds_read_b64_tr_b16 v[128:129], v199 offset:64
	ds_read_b64_tr_b16 v[130:131], v199 offset:704
	ds_read_b64_tr_b16 v[144:145], v199 offset:96
	ds_read_b64_tr_b16 v[146:147], v199 offset:736
	s_waitcnt lgkmcnt(6)
	v_mfma_f32_16x16x32_bf16 v[40:43], v[68:71], v[120:123], v[40:43]
	s_waitcnt lgkmcnt(4)
	v_mfma_f32_16x16x32_bf16 v[44:47], v[68:71], v[124:127], v[44:47]
	s_waitcnt lgkmcnt(2)
	v_mfma_f32_16x16x32_bf16 v[120:123], v[68:71], v[128:131], v[52:55]
	s_waitcnt lgkmcnt(0)
	v_mfma_f32_16x16x32_bf16 v[68:71], v[68:71], v[144:147], v[48:51]
	ds_read_b64_tr_b16 v[124:125], v198 offset:27648
	ds_read_b64_tr_b16 v[126:127], v198 offset:28800
	s_nop 0
	ds_read_b64_tr_b16 v[48:49], v199 offset:5120
	ds_read_b64_tr_b16 v[50:51], v199 offset:5760
	ds_read_b64_tr_b16 v[128:129], v199 offset:5152
	ds_read_b64_tr_b16 v[130:131], v199 offset:5792
	ds_read_b64_tr_b16 v[144:145], v199 offset:5184
	ds_read_b64_tr_b16 v[146:147], v199 offset:5824
	ds_read_b64_tr_b16 v[244:245], v199 offset:5216
	ds_read_b64_tr_b16 v[246:247], v199 offset:5856
	s_waitcnt lgkmcnt(0)
	s_barrier
; __device__ __forceinline__ float bf2f(u16 h) { return __uint_as_float(((uint32_t)h) << 16); }
; __device__ __forceinline__ float ex2(float x) { return __builtin_amdgcn_exp2f(x); }
; __device__ __forceinline__ float silu(float x) { return x * __builtin_amdgcn_rcpf(1.0f + __expf(-x)); }
; template <int DK, int MODE>
; __device__ void rec_prompt_item(const Params& p, const int item, unsigned char* smem) {
;     ...
;     f32x4 in[2];
; #pragma unroll
;     for (int x = 0; x < 2; ++x) in[x] = (f32x4){0.f, 0.f, 0.f, 0.f};
; #pragma unroll
;     for (int ks = 0; ks < 2; ++ks) {
;       const bf16x8 a = *(const bf16x8*)(Ps + (16 * fi + l15) * PS + ks * 64 + g * 16);
;       bf16x8 bv[2];
; #pragma unroll
;       for (int x = 0; x < 2; ++x) bv[x] = trfrag(Vs, VS, 32 * ks, 16 * (fe0 + x), lane);
; #pragma unroll
;       for (int x = 0; x < 2; ++x) in[x] = __builtin_amdgcn_mfma_f32_16x16x32_bf16(a, bv[x], in[x], 0, 0, 0);
;     }
;     {
;       float ss[4] = {0.f, 0.f, 0.f, 0.f};
;       u16* aout = (u16*)(p.ws + OFF_A2);
;       float* parts = (float*)(p.ws + OFF_PARTS);
; #pragma unroll
;       for (int x = 0; x < 2; ++x) {
;         const int e = 16 * (fe0 + x) + l15;
;         const float gn = gnv[x];
;         const int ocol = (MODE == 0) ? (h * 512 + s * 64 + e) : (h * 64 + e);
; #pragma unroll
;         for (int r = 0; r < 4; ++r) {
;           const int i = 16 * fi + 4 * g + r;
;           float o = in[x][r] + cr[x][r] * ex2(ci[r]);
;           const float gv = bf2f(gzc[x][r]);
;           float val;
;           if (MODE == 0) {
;             ss[r] += o * o;
;             val = o * gn * silu(gv);
;           } else {
;             const float xs = bf2f(*(const u16*)(Vs + i * VS + e * 2));
;             const float y = o + xs * dsk;
;             const float gg = y * silu(gv);
;             ss[r] += gg * gg;
;             val = gg * gn;
;           }
;           *(u16*)((char*)aout + (size_t)r0 * 4096 + 32 * x + aoff[r]) = f2bf(val);
;         }
;       }
; #pragma unroll
;       for (int r = 0; r < 4; ++r) {
;         const float v = row16_sum(ss[r]);
;         if (l15 == 0) {
;           const int i = 16 * fi + 4 * g + r;
;           const int slot = (MODE == 0) ? (h * 16 + s * 2 + (w & 1)) : ((h >> 2) * 8 + (h & 3) * 2 + (w & 1));
;           parts[(size_t)(r0 + i) * 64 + slot] = v;
;         }
	v_mfma_f32_16x16x32_bf16 v[52:55], v[124:127], v[48:51], v[40:43]
	v_mfma_f32_16x16x32_bf16 v[48:51], v[124:127], v[128:131], v[44:47]
	v_mfma_f32_16x16x32_bf16 v[44:47], v[124:127], v[144:147], v[120:123]
	v_mfma_f32_16x16x32_bf16 v[40:43], v[124:127], v[244:247], v[68:71]
	s_nop 2
	ds_read_b128 v[68:71], v200
	ds_read_b64_tr_b16 v[120:121], v236 offset:55296
	ds_read_b64_tr_b16 v[122:123], v236 offset:55936
	ds_read_b64_tr_b16 v[124:125], v237 offset:55296
	ds_read_b64_tr_b16 v[126:127], v237 offset:55936
	s_waitcnt lgkmcnt(2)
	v_mfma_f32_16x16x32_bf16 v[120:123], v[68:71], v[120:123], 0
	s_waitcnt lgkmcnt(0)
	v_mfma_f32_16x16x32_bf16 v[68:71], v[68:71], v[124:127], 0
	ds_read_b128 v[124:127], v200 offset:64
	ds_read_b64_tr_b16 v[128:129], v235 offset:55296
	ds_read_b64_tr_b16 v[130:131], v235 offset:55936
	ds_read_b64_tr_b16 v[144:145], v238 offset:55296
	ds_read_b64_tr_b16 v[146:147], v238 offset:55936
	s_waitcnt lgkmcnt(2)
	v_mfma_f32_16x16x32_bf16 v[120:123], v[124:127], v[128:131], v[120:123]
	v_exp_f32_e32 v128, v64
	v_lshlrev_b32_e32 v64, 16, v230
	s_waitcnt lgkmcnt(0)
	v_mfma_f32_16x16x32_bf16 v[68:71], v[124:127], v[144:147], v[68:71]
	v_add_co_u32_e32 v124, vcc, s67, v134
	s_nop 2
	v_fma_f32 v60, v60, v128, v120
	ds_read_u16 v120, v201 offset:55296
	v_addc_co_u32_e32 v125, vcc, 0, v135, vcc
	v_fmac_f32_e32 v123, v63, v67
	v_fma_f32 v56, v56, v128, v68
	s_waitcnt lgkmcnt(0)
	v_lshlrev_b32_e32 v120, 16, v120
	v_fmac_f32_e32 v60, v74, v120
	v_mul_f32_e32 v120, 0xbfb8aa3b, v64
	v_exp_f32_e32 v120, v120
	v_lshlrev_b32_e32 v68, 16, v218
	v_fmac_f32_e32 v71, v59, v67
	v_add_f32_e32 v120, 1.0, v120
	v_rcp_f32_e32 v120, v120
	s_nop 0
	v_mul_f32_e32 v64, v120, v64
	v_mul_f32_e32 v129, v64, v60
	ds_read_u16 v64, v201 offset:55456
	v_mul_f32_e32 v60, v203, v129
	v_cvt_pk_bf16_f32 v60, v60, s0
	global_store_short v[124:125], v60, off
	v_fma_f32 v60, v61, v65, v121
	v_lshlrev_b32_e32 v61, 16, v229
	s_waitcnt lgkmcnt(0)
	v_lshlrev_b32_e32 v64, 16, v64
	v_fmac_f32_e32 v60, v74, v64
	v_mul_f32_e32 v64, 0xbfb8aa3b, v61
	v_exp_f32_e32 v64, v64
	v_add_co_u32_e32 v120, vcc, s67, v136
	v_add_f32_e32 v64, 1.0, v64
	v_rcp_f32_e32 v64, v64
	v_addc_co_u32_e32 v121, vcc, 0, v137, vcc
	v_add_co_u32_e32 v126, vcc, s67, v138
	v_mul_f32_e32 v61, v64, v61
	v_mul_f32_e32 v64, v61, v60
	v_mul_f32_e32 v60, v203, v64
	v_cvt_pk_bf16_f32 v60, v60, s0
	global_store_short v[120:121], v60, off
	v_fma_f32 v60, v62, v66, v122
	ds_read_u16 v62, v201 offset:55616
	v_lshlrev_b32_e32 v61, 16, v228
	v_addc_co_u32_e32 v127, vcc, 0, v139, vcc
	s_waitcnt lgkmcnt(0)
	v_lshlrev_b32_e32 v62, 16, v62
	v_fmac_f32_e32 v60, v74, v62
	v_mul_f32_e32 v62, 0xbfb8aa3b, v61
	v_exp_f32_e32 v62, v62
	s_nop 0
	v_add_f32_e32 v62, 1.0, v62
	v_rcp_f32_e32 v62, v62
	s_nop 0
	v_mul_f32_e32 v61, v62, v61
	v_mul_f32_e32 v62, v61, v60
	ds_read_u16 v61, v201 offset:55776
	v_mul_f32_e32 v60, v203, v62
	v_cvt_pk_bf16_f32 v60, v60, s0
	global_store_short v[126:127], v60, off
	v_lshlrev_b32_e32 v60, 16, v219
	s_waitcnt lgkmcnt(0)
	v_lshlrev_b32_e32 v61, 16, v61
	v_fmac_f32_e32 v123, v74, v61
	v_mul_f32_e32 v61, 0xbfb8aa3b, v60
	v_exp_f32_e32 v61, v61
	s_nop 0
	v_add_f32_e32 v61, 1.0, v61
	v_rcp_f32_e32 v61, v61
	s_nop 0
	v_mul_f32_e32 v60, v61, v60
	v_mul_f32_e32 v63, v60, v123
	v_mul_f32_e32 v60, v203, v63
	v_cvt_pk_bf16_f32 v122, v60, s0
	v_add_co_u32_e32 v60, vcc, s67, v140
	s_nop 1
	v_addc_co_u32_e32 v61, vcc, 0, v141, vcc
	global_store_short v[60:61], v122, off
	ds_read_u16 v122, v202 offset:55296
	s_waitcnt lgkmcnt(0)
	v_lshlrev_b32_e32 v122, 16, v122
	v_fmac_f32_e32 v56, v74, v122
	v_mul_f32_e32 v122, 0xbfb8aa3b, v68
	v_exp_f32_e32 v122, v122
	s_nop 0
	v_add_f32_e32 v122, 1.0, v122
	v_rcp_f32_e32 v122, v122
	s_nop 0
	v_mul_f32_e32 v68, v122, v68
	v_mul_f32_e32 v56, v68, v56
	v_mul_f32_e32 v68, v56, v56
	v_mul_f32_e32 v56, v204, v56
	v_cvt_pk_bf16_f32 v56, v56, s0
	global_store_short v[124:125], v56, off offset:32
	v_fma_f32 v56, v57, v65, v69
	ds_read_u16 v65, v202 offset:55456
	v_lshlrev_b32_e32 v57, 16, v217
	v_fmac_f32_e32 v68, v129, v129
	s_waitcnt lgkmcnt(0)
	v_lshlrev_b32_e32 v65, 16, v65
	v_fmac_f32_e32 v56, v74, v65
	v_mul_f32_e32 v65, 0xbfb8aa3b, v57
	v_exp_f32_e32 v65, v65
	s_nop 0
	v_add_f32_e32 v65, 1.0, v65
	v_rcp_f32_e32 v65, v65
	s_nop 0
	v_mul_f32_e32 v57, v65, v57
	v_mul_f32_e32 v65, v57, v56
	v_mul_f32_e32 v56, v204, v65
	v_cvt_pk_bf16_f32 v56, v56, s0
	global_store_short v[120:121], v56, off offset:32
	v_fma_f32 v56, v58, v66, v70
	ds_read_u16 v58, v202 offset:55616
	v_lshlrev_b32_e32 v57, 16, v216
	s_waitcnt lgkmcnt(0)
	v_lshlrev_b32_e32 v58, 16, v58
	v_fmac_f32_e32 v56, v74, v58
	v_mul_f32_e32 v58, 0xbfb8aa3b, v57
	v_exp_f32_e32 v58, v58
	s_nop 0
	v_add_f32_e32 v58, 1.0, v58
	v_rcp_f32_e32 v58, v58
	s_nop 0
	v_mul_f32_e32 v57, v58, v57
	v_mul_f32_e32 v58, v57, v56
	ds_read_u16 v57, v202 offset:55776
	v_mul_f32_e32 v56, v204, v58
	v_cvt_pk_bf16_f32 v56, v56, s0
	global_store_short v[126:127], v56, off offset:32
	v_lshlrev_b32_e32 v56, 16, v215
	s_waitcnt lgkmcnt(0)
	v_lshlrev_b32_e32 v57, 16, v57
	v_fmac_f32_e32 v71, v74, v57
	v_mul_f32_e32 v57, 0xbfb8aa3b, v56
	v_exp_f32_e32 v57, v57
	s_nop 0
	v_add_f32_e32 v57, 1.0, v57
	v_rcp_f32_e32 v57, v57
	s_nop 0
	v_mul_f32_e32 v56, v57, v56
	v_mul_f32_e32 v59, v56, v71
	v_mul_f32_e32 v56, v204, v59
	v_cvt_pk_bf16_f32 v56, v56, s0
	global_store_short v[60:61], v56, off offset:32
	s_nop 0
	v_add_f32_dpp v56, v68, v68 quad_perm:[1,0,3,2] row_mask:0xf bank_mask:0xf bound_ctrl:1
	s_nop 1
	v_add_f32_dpp v56, v56, v56 quad_perm:[2,3,0,1] row_mask:0xf bank_mask:0xf bound_ctrl:1
	s_nop 1
	v_add_f32_dpp v60, v56, v56 row_ror:4 row_mask:0xf bank_mask:0xf bound_ctrl:1
	v_lshl_add_u64 v[56:57], v[110:111], 0, s[24:25]
	s_nop 0
	v_mov_b32_dpp v61, v60 row_ror:8 row_mask:0xf bank_mask:0xf bound_ctrl:1
	s_and_saveexec_b64 s[46:47], s[4:5]
	s_cbranch_execz .LBB0_1729
	v_add_f32_e32 v60, v60, v61
	global_store_dword v[56:57], v60, off offset:-512
